# v29 + counted LDS waits inside the MFMA blocks of the projection K-loop (the loading wave reaches the hand-off barrier without waiting for its LDS-read tail)
# speedup vs baseline: 1.0123x; 1.0059x over previous
.Lrw_done_a:
	s_setprio 1
	s_barrier
	s_waitcnt lgkmcnt(7)
	v_mfma_f32_16x16x32_bf16 v[148:151], v[36:39], v[190:193], 0
	v_mfma_f32_16x16x32_bf16 v[152:155], v[84:87], v[190:193], 0
	s_waitcnt lgkmcnt(5)
	v_mfma_f32_16x16x32_bf16 v[128:131], v[36:39], v[198:201], 0
	v_mfma_f32_16x16x32_bf16 v[132:135], v[84:87], v[198:201], 0
	s_waitcnt lgkmcnt(3)
	v_mfma_f32_16x16x32_bf16 v[108:111], v[36:39], v[206:209], 0
	v_mfma_f32_16x16x32_bf16 v[112:115], v[84:87], v[206:209], 0
	s_waitcnt lgkmcnt(1)
	v_mfma_f32_16x16x32_bf16 v[88:91], v[36:39], v[214:217], 0
	v_mfma_f32_16x16x32_bf16 v[92:95], v[84:87], v[214:217], 0
	v_mfma_f32_16x16x32_bf16 v[148:151], v[56:59], v[194:197], v[148:151]
	v_mfma_f32_16x16x32_bf16 v[152:155], v[104:107], v[194:197], v[152:155]
	v_mfma_f32_16x16x32_bf16 v[128:131], v[56:59], v[202:205], v[128:131]
	v_mfma_f32_16x16x32_bf16 v[132:135], v[104:107], v[202:205], v[132:135]
	v_mfma_f32_16x16x32_bf16 v[108:111], v[56:59], v[210:213], v[108:111]
	v_mfma_f32_16x16x32_bf16 v[112:115], v[104:107], v[210:213], v[112:115]
	s_waitcnt lgkmcnt(0)
	v_mfma_f32_16x16x32_bf16 v[88:91], v[56:59], v[218:221], v[88:91]
	v_mfma_f32_16x16x32_bf16 v[92:95], v[104:107], v[218:221], v[92:95]
	s_setprio 0
	s_setprio 1
	v_mfma_f32_16x16x32_bf16 v[140:143], v[124:127], v[190:193], 0
	v_mfma_f32_16x16x32_bf16 v[136:139], v[156:159], v[190:193], 0
	v_mfma_f32_16x16x32_bf16 v[120:123], v[124:127], v[198:201], 0
	v_mfma_f32_16x16x32_bf16 v[116:119], v[156:159], v[198:201], 0
	v_mfma_f32_16x16x32_bf16 v[100:103], v[124:127], v[206:209], 0
	v_mfma_f32_16x16x32_bf16 v[96:99], v[156:159], v[206:209], 0
	v_mfma_f32_16x16x32_bf16 v[80:83], v[124:127], v[214:217], 0
	v_mfma_f32_16x16x32_bf16 v[76:79], v[156:159], v[214:217], 0
	v_mfma_f32_16x16x32_bf16 v[140:143], v[144:147], v[194:197], v[140:143]
	v_mfma_f32_16x16x32_bf16 v[136:139], v[180:183], v[194:197], v[136:139]
	v_mfma_f32_16x16x32_bf16 v[120:123], v[144:147], v[202:205], v[120:123]
	v_mfma_f32_16x16x32_bf16 v[116:119], v[180:183], v[202:205], v[116:119]
	v_mfma_f32_16x16x32_bf16 v[100:103], v[144:147], v[210:213], v[100:103]
	v_mfma_f32_16x16x32_bf16 v[96:99], v[180:183], v[210:213], v[96:99]
	v_mfma_f32_16x16x32_bf16 v[80:83], v[144:147], v[218:221], v[80:83]
	v_mfma_f32_16x16x32_bf16 v[76:79], v[180:183], v[218:221], v[76:79]
	s_barrier
	s_setprio 0
	s_add_i32 s72, s95, s16
	v_lshl_add_u64 v[226:227], s[76:77], 0, v[164:165]
	s_mov_b32 m0, s72
	ds_read_b128 v[190:193], v188 offset:16384
	ds_read_b128 v[194:197], v188 offset:17408
	ds_read_b128 v[198:201], v188 offset:18432
	ds_read_b128 v[202:205], v188 offset:19456
	ds_read_b128 v[206:209], v188 offset:20480
	ds_read_b128 v[210:213], v188 offset:21504
	ds_read_b128 v[214:217], v188 offset:22528
	ds_read_b128 v[218:221], v188 offset:23552
	global_load_lds_dwordx4 v[226:227], off
	s_add_i32 m0, s72, 0x2000
	s_add_u32 s72, s76, 0x40000
	v_lshl_add_u64 v[228:229], s[76:77], 0, v[160:161]
	s_addc_u32 s73, s77, 0
	s_add_i32 s12, s12, s16
	global_load_lds_dwordx4 v[228:229], off
	v_lshl_add_u64 v[230:231], s[72:73], 0, v[164:165]
	s_mov_b32 m0, s12
	v_lshl_add_u64 v[232:233], s[78:79], 0, v[162:163]
	global_load_lds_dwordx4 v[230:231], off
	v_lshl_add_u64 v[230:231], s[72:73], 0, v[160:161]
	s_add_i32 m0, s12, 0x2000
	s_nop 0
	global_load_lds_dwordx4 v[230:231], off
	v_lshl_add_u64 v[230:231], s[78:79], 0, v[166:167]
	s_mov_b32 m0, s17
	s_nop 0
	global_load_lds_dwordx4 v[230:231], off
	s_mov_b32 m0, s46
	s_nop 0
	global_load_lds_dwordx4 v[232:233], off
	s_cmp_eq_u32 s98, 0
	s_cbranch_scc1 .Lrw_strict_b
	s_waitcnt vmcnt(24)
	s_branch .Lrw_done_b

.Lrw_done_b:
	s_setprio 1
	s_barrier
	s_waitcnt lgkmcnt(7)
	v_mfma_f32_16x16x32_bf16 v[68:71], v[36:39], v[190:193], 0
	v_mfma_f32_16x16x32_bf16 v[72:75], v[84:87], v[190:193], 0
	s_waitcnt lgkmcnt(5)
	v_mfma_f32_16x16x32_bf16 v[48:51], v[36:39], v[198:201], 0
	v_mfma_f32_16x16x32_bf16 v[52:55], v[84:87], v[198:201], 0
	s_waitcnt lgkmcnt(3)
	v_mfma_f32_16x16x32_bf16 v[28:31], v[36:39], v[206:209], 0
	v_mfma_f32_16x16x32_bf16 v[32:35], v[84:87], v[206:209], 0
	s_waitcnt lgkmcnt(1)
	v_mfma_f32_16x16x32_bf16 v[10:13], v[36:39], v[214:217], 0
	v_mfma_f32_16x16x32_bf16 v[14:17], v[84:87], v[214:217], 0
	v_mfma_f32_16x16x32_bf16 v[68:71], v[56:59], v[194:197], v[68:71]
	v_mfma_f32_16x16x32_bf16 v[72:75], v[104:107], v[194:197], v[72:75]
	v_mfma_f32_16x16x32_bf16 v[48:51], v[56:59], v[202:205], v[48:51]
	v_mfma_f32_16x16x32_bf16 v[52:55], v[104:107], v[202:205], v[52:55]
	v_mfma_f32_16x16x32_bf16 v[28:31], v[56:59], v[210:213], v[28:31]
	v_mfma_f32_16x16x32_bf16 v[32:35], v[104:107], v[210:213], v[32:35]
	s_waitcnt lgkmcnt(0)
	v_mfma_f32_16x16x32_bf16 v[10:13], v[56:59], v[218:221], v[10:13]
	v_mfma_f32_16x16x32_bf16 v[14:17], v[104:107], v[218:221], v[14:17]
	s_setprio 0
	s_setprio 1
	v_mfma_f32_16x16x32_bf16 v[44:47], v[124:127], v[198:201], 0
	v_mfma_f32_16x16x32_bf16 v[40:43], v[156:159], v[198:201], 0
	v_mfma_f32_16x16x32_bf16 v[22:25], v[124:127], v[206:209], 0
	v_mfma_f32_16x16x32_bf16 v[18:21], v[156:159], v[206:209], 0
	v_mfma_f32_16x16x32_bf16 v[2:5], v[124:127], v[214:217], 0
	v_mfma_f32_16x16x32_bf16 v[6:9], v[156:159], v[214:217], 0
	v_mfma_f32_16x16x32_bf16 v[36:39], v[124:127], v[190:193], 0
	v_mfma_f32_16x16x32_bf16 v[56:59], v[156:159], v[190:193], 0
	v_mfma_f32_16x16x32_bf16 v[44:47], v[144:147], v[202:205], v[44:47]
	v_mfma_f32_16x16x32_bf16 v[40:43], v[180:183], v[202:205], v[40:43]
	v_mfma_f32_16x16x32_bf16 v[22:25], v[144:147], v[210:213], v[22:25]
	v_mfma_f32_16x16x32_bf16 v[18:21], v[180:183], v[210:213], v[18:21]
	v_mfma_f32_16x16x32_bf16 v[2:5], v[144:147], v[218:221], v[2:5]
	v_mfma_f32_16x16x32_bf16 v[6:9], v[180:183], v[218:221], v[6:9]
	v_mfma_f32_16x16x32_bf16 v[36:39], v[144:147], v[194:197], v[36:39]
	v_mfma_f32_16x16x32_bf16 v[56:59], v[180:183], v[194:197], v[56:59]
	s_barrier
	s_setprio 0
	s_add_i32 s12, 0, 0x18000
	v_add_u32_e32 v26, s12, v186
	s_add_i32 s95, 0, 0x1c000
	ds_read_b128 v[60:63], v26
	ds_read_b128 v[64:67], v26 offset:1024
	ds_read_b128 v[84:87], v26 offset:2048
	ds_read_b128 v[104:107], v26 offset:3072
	v_add_u32_e32 v26, s95, v186
	ds_read_b128 v[124:127], v26
	ds_read_b128 v[144:147], v26 offset:1024
	ds_read_b128 v[156:159], v26 offset:2048
	ds_read_b128 v[180:183], v26 offset:3072
	s_add_u32 s72, s78, 0x160000
	s_addc_u32 s73, s79, 0
	s_mov_b32 m0, s47
	v_lshl_add_u64 v[234:235], s[72:73], 0, v[166:167]
	ds_read_b128 v[190:193], v188 offset:32768
	ds_read_b128 v[194:197], v188 offset:33792
	ds_read_b128 v[198:201], v188 offset:34816
	ds_read_b128 v[202:205], v188 offset:35840
	ds_read_b128 v[206:209], v188 offset:36864
	ds_read_b128 v[210:213], v188 offset:37888
	ds_read_b128 v[214:217], v188 offset:38912
	ds_read_b128 v[218:221], v188 offset:39936
	global_load_lds_dwordx4 v[234:235], off
	v_lshl_add_u64 v[234:235], s[72:73], 0, v[162:163]
	s_mov_b32 m0, s8
	s_nop 0
	global_load_lds_dwordx4 v[234:235], off
	s_waitcnt vmcnt(8)
	s_setprio 1
	s_barrier
	s_waitcnt lgkmcnt(7)
	v_mfma_f32_16x16x32_bf16 v[148:151], v[60:63], v[190:193], v[148:151]
	v_mfma_f32_16x16x32_bf16 v[152:155], v[84:87], v[190:193], v[152:155]
	s_waitcnt lgkmcnt(5)
	v_mfma_f32_16x16x32_bf16 v[128:131], v[60:63], v[198:201], v[128:131]
	v_mfma_f32_16x16x32_bf16 v[132:135], v[84:87], v[198:201], v[132:135]
	s_waitcnt lgkmcnt(3)
	v_mfma_f32_16x16x32_bf16 v[108:111], v[60:63], v[206:209], v[108:111]
	v_mfma_f32_16x16x32_bf16 v[112:115], v[84:87], v[206:209], v[112:115]
	s_waitcnt lgkmcnt(1)
	v_mfma_f32_16x16x32_bf16 v[88:91], v[60:63], v[214:217], v[88:91]
	v_mfma_f32_16x16x32_bf16 v[92:95], v[84:87], v[214:217], v[92:95]
	v_mfma_f32_16x16x32_bf16 v[148:151], v[64:67], v[194:197], v[148:151]
	v_mfma_f32_16x16x32_bf16 v[152:155], v[104:107], v[194:197], v[152:155]
	v_mfma_f32_16x16x32_bf16 v[128:131], v[64:67], v[202:205], v[128:131]
	v_mfma_f32_16x16x32_bf16 v[132:135], v[104:107], v[202:205], v[132:135]
	v_mfma_f32_16x16x32_bf16 v[108:111], v[64:67], v[210:213], v[108:111]
	v_mfma_f32_16x16x32_bf16 v[112:115], v[104:107], v[210:213], v[112:115]
	s_waitcnt lgkmcnt(0)
	v_mfma_f32_16x16x32_bf16 v[88:91], v[64:67], v[218:221], v[88:91]
	v_mfma_f32_16x16x32_bf16 v[92:95], v[104:107], v[218:221], v[92:95]
	s_setprio 0
	s_setprio 1
	v_mfma_f32_16x16x32_bf16 v[140:143], v[124:127], v[190:193], v[140:143]
	v_mfma_f32_16x16x32_bf16 v[136:139], v[156:159], v[190:193], v[136:139]
	v_mfma_f32_16x16x32_bf16 v[120:123], v[124:127], v[198:201], v[120:123]
	v_mfma_f32_16x16x32_bf16 v[116:119], v[156:159], v[198:201], v[116:119]
	v_mfma_f32_16x16x32_bf16 v[100:103], v[124:127], v[206:209], v[100:103]
	v_mfma_f32_16x16x32_bf16 v[96:99], v[156:159], v[206:209], v[96:99]
	v_mfma_f32_16x16x32_bf16 v[80:83], v[124:127], v[214:217], v[80:83]
	v_mfma_f32_16x16x32_bf16 v[76:79], v[156:159], v[214:217], v[76:79]
	v_mfma_f32_16x16x32_bf16 v[140:143], v[144:147], v[194:197], v[140:143]
	v_mfma_f32_16x16x32_bf16 v[136:139], v[180:183], v[194:197], v[136:139]
	v_mfma_f32_16x16x32_bf16 v[120:123], v[144:147], v[202:205], v[120:123]
	v_mfma_f32_16x16x32_bf16 v[116:119], v[180:183], v[202:205], v[116:119]
	v_mfma_f32_16x16x32_bf16 v[100:103], v[144:147], v[210:213], v[100:103]
	v_mfma_f32_16x16x32_bf16 v[96:99], v[180:183], v[210:213], v[96:99]
	v_mfma_f32_16x16x32_bf16 v[80:83], v[144:147], v[218:221], v[80:83]
	v_mfma_f32_16x16x32_bf16 v[76:79], v[180:183], v[218:221], v[76:79]
	s_barrier
	s_setprio 0
	s_add_i32 s12, s12, s16
	v_lshl_add_u64 v[226:227], v[226:227], 0, s[82:83]
	s_mov_b32 m0, s12
	ds_read_b128 v[190:193], v188 offset:49152
	ds_read_b128 v[194:197], v188 offset:50176
	ds_read_b128 v[198:201], v188 offset:51200
	ds_read_b128 v[202:205], v188 offset:52224
	ds_read_b128 v[206:209], v188 offset:53248
	ds_read_b128 v[210:213], v188 offset:54272
	ds_read_b128 v[214:217], v188 offset:55296
	ds_read_b128 v[218:221], v188 offset:56320
	global_load_lds_dwordx4 v[226:227], off
	s_add_i32 m0, s12, 0x2000
	s_add_u32 s72, s76, 0x40080
	v_lshl_add_u64 v[226:227], v[228:229], 0, s[82:83]
	s_addc_u32 s73, s77, 0
	s_add_i32 s12, s95, s16
	global_load_lds_dwordx4 v[226:227], off
	v_lshl_add_u64 v[226:227], s[72:73], 0, v[164:165]
	s_mov_b32 m0, s12
	s_nop 0
	global_load_lds_dwordx4 v[226:227], off
	v_lshl_add_u64 v[226:227], s[72:73], 0, v[160:161]
	s_add_i32 m0, s12, 0x2000
	s_nop 0
	global_load_lds_dwordx4 v[226:227], off
	v_lshl_add_u64 v[226:227], v[230:231], 0, s[82:83]
	s_mov_b32 m0, s22
	s_nop 0
	global_load_lds_dwordx4 v[226:227], off
	v_lshl_add_u64 v[226:227], v[232:233], 0, s[82:83]
	s_mov_b32 m0, s80
	s_nop 0
	global_load_lds_dwordx4 v[226:227], off
	s_waitcnt vmcnt(8)
	s_setprio 1
	s_barrier
	s_waitcnt lgkmcnt(7)
	v_mfma_f32_16x16x32_bf16 v[68:71], v[60:63], v[190:193], v[68:71]
	v_mfma_f32_16x16x32_bf16 v[72:75], v[84:87], v[190:193], v[72:75]
	s_waitcnt lgkmcnt(5)
	v_mfma_f32_16x16x32_bf16 v[48:51], v[60:63], v[198:201], v[48:51]
	v_mfma_f32_16x16x32_bf16 v[52:55], v[84:87], v[198:201], v[52:55]
	s_waitcnt lgkmcnt(3)
	v_mfma_f32_16x16x32_bf16 v[28:31], v[60:63], v[206:209], v[28:31]
	v_mfma_f32_16x16x32_bf16 v[32:35], v[84:87], v[206:209], v[32:35]
	s_waitcnt lgkmcnt(1)
	v_mfma_f32_16x16x32_bf16 v[10:13], v[60:63], v[214:217], v[10:13]
	v_mfma_f32_16x16x32_bf16 v[14:17], v[84:87], v[214:217], v[14:17]
	v_mfma_f32_16x16x32_bf16 v[68:71], v[64:67], v[194:197], v[68:71]
	v_mfma_f32_16x16x32_bf16 v[72:75], v[104:107], v[194:197], v[72:75]
	v_mfma_f32_16x16x32_bf16 v[48:51], v[64:67], v[202:205], v[48:51]
	v_mfma_f32_16x16x32_bf16 v[52:55], v[104:107], v[202:205], v[52:55]
	v_mfma_f32_16x16x32_bf16 v[28:31], v[64:67], v[210:213], v[28:31]
	v_mfma_f32_16x16x32_bf16 v[32:35], v[104:107], v[210:213], v[32:35]
	s_waitcnt lgkmcnt(0)
	v_mfma_f32_16x16x32_bf16 v[10:13], v[64:67], v[218:221], v[10:13]
	v_mfma_f32_16x16x32_bf16 v[14:17], v[104:107], v[218:221], v[14:17]
	s_setprio 0
	s_setprio 1
	v_mfma_f32_16x16x32_bf16 v[36:39], v[124:127], v[190:193], v[36:39]
	v_mfma_f32_16x16x32_bf16 v[64:67], v[144:147], v[194:197], v[36:39]
	v_mfma_f32_16x16x32_bf16 v[36:39], v[156:159], v[190:193], v[56:59]
	v_mfma_f32_16x16x32_bf16 v[60:63], v[180:183], v[194:197], v[36:39]
	v_mfma_f32_16x16x32_bf16 v[36:39], v[124:127], v[198:201], v[44:47]
	v_mfma_f32_16x16x32_bf16 v[44:47], v[144:147], v[202:205], v[36:39]
	v_mfma_f32_16x16x32_bf16 v[36:39], v[156:159], v[198:201], v[40:43]
	v_mfma_f32_16x16x32_bf16 v[22:25], v[124:127], v[206:209], v[22:25]
	v_mfma_f32_16x16x32_bf16 v[18:21], v[156:159], v[206:209], v[18:21]
	v_mfma_f32_16x16x32_bf16 v[2:5], v[124:127], v[214:217], v[2:5]
	v_mfma_f32_16x16x32_bf16 v[6:9], v[156:159], v[214:217], v[6:9]
	v_mfma_f32_16x16x32_bf16 v[40:43], v[180:183], v[202:205], v[36:39]
	v_mfma_f32_16x16x32_bf16 v[22:25], v[144:147], v[210:213], v[22:25]
	v_mfma_f32_16x16x32_bf16 v[18:21], v[180:183], v[210:213], v[18:21]
	v_mfma_f32_16x16x32_bf16 v[2:5], v[144:147], v[218:221], v[2:5]
	v_mfma_f32_16x16x32_bf16 v[6:9], v[180:183], v[218:221], v[6:9]
	s_barrier
	s_setprio 0
	s_add_i32 s93, s93, 2
	s_add_u32 vcc_lo, vcc_lo, 0x100
	s_addc_u32 vcc_hi, vcc_hi, 0
	s_add_u32 s84, s84, 0x100
	s_addc_u32 s85, s85, 0
